# fox loop header: negated wave-uniform masks via s_andn2 instead of v_cndmask+v_cmp
# baseline (speedup 1.0000x reference)
; #define LAS __attribute__((address_space(3)))
; template <bool FOX> ...
;     ...
;         const int tn = FOX ? t - 1 : t + 1, tn2 = FOX ? t - 2 : t + 2;
;         const bool have_next = FOX ? (tn >= 1) : (tn <= NT), have_next2 = FOX ? (tn2 >= 1) : (tn2 <= NT);
;         const int nbuf = (buf + 1) & 3;
;         const bool act = (t <= tq) && wmore;
;         LAS const unsigned char* vbp_ = lds + pbuf * 32768;
;         LAS const unsigned char* kb = lds + buf * 32768;
;         s16x4 va[NCB][2];
;         f32x16 s0, s1;
;         float ckfirst = 0.f, alpha_o = 1.f; bool resc = false;
;         if (act) {
;             bf16x8 kf[8];
; #pragma unroll
;             for (int s = 0; s < 4; ++s) { kf[2 * s] = *(LAS const bf16x8*)(kb + koff[s]); kf[2 * s + 1] = *(LAS const bf16x8*)(kb + koff[s] + 8192); }
;             if (have_next2) ATT_DMA(tn2, (buf + 2) & 3);
.LBB0_500:
	s_add_i32 s34, s0, -1
	s_cmp_gt_i32 s34, 2
	s_mov_b32 s18, s3
	s_cselect_b64 s[2:3], -1, 0
	s_cmp_lt_i32 s34, 3
	s_cselect_b64 s[28:29], -1, 0
	s_cmp_le_i32 s34, s1
	s_cselect_b64 s[12:13], -1, 0
	s_and_b64 s[40:41], s[12:13], s[20:21]
	s_andn2_b64 s[12:13], exec, s[40:41]
	s_andn2_b64 s[14:15], exec, s[2:3]
	s_andn2_b64 vcc, exec, s[40:41]
	s_mov_b64 s[2:3], -1
	s_cbranch_vccz .LBB0_504
	s_and_b64 vcc, exec, s[14:15]
	s_cbranch_vccnz .LBB0_503
	s_xor_b32 s19, s18, 2
	s_lshl_b32 s2, s19, 15
	s_add_i32 vcc_lo, s30, s2
	s_lshl_b64 s[2:3], s[16:17], 10
	v_lshl_add_u64 v[2:3], v[140:141], 0, s[2:3]
	s_mov_b32 m0, vcc_lo
	s_nop 0
	global_load_lds_dwordx4 v[2:3], off
	v_lshl_add_u64 v[2:3], v[144:145], 0, s[2:3]
	s_add_i32 m0, vcc_lo, 0x400
	s_nop 0
	global_load_lds_dwordx4 v[2:3], off
	v_lshl_add_u64 v[2:3], v[138:139], 0, s[2:3]
	s_add_i32 m0, vcc_lo, 0x4000
	s_nop 0
	global_load_lds_dwordx4 v[2:3], off
	v_lshl_add_u64 v[2:3], v[142:143], 0, s[2:3]
	s_add_i32 m0, vcc_lo, 0x4400
	s_lshl_b64 s[2:3], s[16:17], 5
	global_load_lds_dwordx4 v[2:3], off
	v_lshl_add_u64 v[2:3], v[146:147], 0, s[2:3]
	s_lshl_b32 s2, s19, 9
	s_add_i32 m0, s31, s2
	s_nop 0
	global_load_lds_dword v[2:3], off
